# score tile: second-half MFMAs interleaved into the per-query VALU work
# baseline (speedup 1.0000x reference)
.Lsc_step:
	s_sub_i32 s10, s9, 24
	s_waitcnt vmcnt(6)
	v_mfma_f32_16x16x32_bf16 v[114:117], v[94:97], v[158:161], 0
	v_mfma_f32_16x16x32_bf16 v[118:121], v[82:85], v[158:161], 0
	v_mfma_f32_16x16x32_bf16 v[122:125], v[70:73], v[158:161], 0
	v_mfma_f32_16x16x32_bf16 v[126:129], v[58:61], v[158:161], 0
	v_mfma_f32_16x16x32_bf16 v[130:133], v[46:49], v[158:161], 0
	v_mfma_f32_16x16x32_bf16 v[134:137], v[34:37], v[158:161], 0
	v_mfma_f32_16x16x32_bf16 v[138:141], v[22:25], v[158:161], 0
	v_mfma_f32_16x16x32_bf16 v[142:145], v[10:13], v[158:161], 0
	v_mfma_f32_16x16x32_bf16 v[114:117], v[90:93], v[154:157], v[114:117]
	v_mfma_f32_16x16x32_bf16 v[118:121], v[78:81], v[154:157], v[118:121]
	v_mfma_f32_16x16x32_bf16 v[122:125], v[66:69], v[154:157], v[122:125]
	v_mfma_f32_16x16x32_bf16 v[126:129], v[54:57], v[154:157], v[126:129]
	v_add_u32_e32 v234, 0xfffffe80, v5
	v_cmp_le_i32_e64 s[90:91], v234, v0
	v_cmp_le_i32_e64 s[92:93], v234, v223
	v_add_u32_e32 v237, 0x10000, v4
	s_nop 1
	v_max_i32_e32 v226, 0, v115
	v_max_i32_e32 v228, 0, v119
	v_max_i32_e32 v227, 0, v116
	v_max_i32_e32 v229, 0, v120
	v_mfma_f32_16x16x32_bf16 v[130:133], v[42:45], v[154:157], v[130:133]
	v_max_i32_e32 v115, 0, v117
	v_max_i32_e32 v119, 0, v121
	v_max_i32_e32 v114, 0, v114
	v_max_i32_e32 v118, 0, v118
	v_pk_mul_f32 v[114:115], v[86:87], v[114:115]
	v_pk_mul_f32 v[118:119], v[74:75], v[118:119]
	v_mfma_f32_16x16x32_bf16 v[134:137], v[30:33], v[154:157], v[134:137]
	v_pk_fma_f32 v[226:227], v[184:185], v[226:227], v[114:115]
	v_pk_fma_f32 v[228:229], v[88:89], v[228:229], v[118:119]
	v_add_f32_e32 v116, v226, v227
	v_add_f32_e32 v120, v228, v229
	v_max_i32_e32 v226, 0, v123
	v_max_i32_e32 v228, 0, v127
	v_max_i32_e32 v227, 0, v124
	v_max_i32_e32 v229, 0, v128
	v_mfma_f32_16x16x32_bf16 v[138:141], v[18:21], v[154:157], v[138:141]
	v_max_i32_e32 v123, 0, v125
	v_max_i32_e32 v127, 0, v129
	v_max_i32_e32 v122, 0, v122
	v_max_i32_e32 v126, 0, v126
	v_pk_mul_f32 v[122:123], v[62:63], v[122:123]
	v_pk_mul_f32 v[126:127], v[50:51], v[126:127]
	v_mfma_f32_16x16x32_bf16 v[142:145], v[6:9], v[154:157], v[142:145]
	v_pk_fma_f32 v[226:227], v[76:77], v[226:227], v[122:123]
	v_pk_fma_f32 v[228:229], v[64:65], v[228:229], v[126:127]
	v_add_f32_e32 v124, v226, v227
	v_add_f32_e32 v128, v228, v229
	s_cmp_lt_i32 s10, s6
	s_cbranch_scc0 .Lsc_np0
	global_load_dwordx4 v[158:161], v[180:181], off
	global_load_dwordx4 v[154:157], v[180:181], off offset:64
.Lsc_np0:
	v_max_i32_e32 v226, 0, v131
	v_max_i32_e32 v228, 0, v135
	v_max_i32_e32 v227, 0, v132
	v_max_i32_e32 v229, 0, v136
	v_max_i32_e32 v131, 0, v133
	v_max_i32_e32 v135, 0, v137
	v_max_i32_e32 v130, 0, v130
	v_max_i32_e32 v134, 0, v134
	v_pk_mul_f32 v[130:131], v[38:39], v[130:131]
	v_pk_mul_f32 v[134:135], v[26:27], v[134:135]
	v_pk_fma_f32 v[226:227], v[52:53], v[226:227], v[130:131]
	v_pk_fma_f32 v[228:229], v[40:41], v[228:229], v[134:135]
	v_add_f32_e32 v132, v226, v227
	v_add_f32_e32 v136, v228, v229
	v_max_i32_e32 v226, 0, v139
	v_max_i32_e32 v228, 0, v143
	v_max_i32_e32 v227, 0, v140
	v_max_i32_e32 v229, 0, v144
	v_max_i32_e32 v139, 0, v141
	v_max_i32_e32 v143, 0, v145
	v_max_i32_e32 v138, 0, v138
	v_max_i32_e32 v142, 0, v142
	v_pk_mul_f32 v[138:139], v[14:15], v[138:139]
	v_pk_mul_f32 v[142:143], v[2:3], v[142:143]
	v_pk_fma_f32 v[226:227], v[28:29], v[226:227], v[138:139]
	v_pk_fma_f32 v[228:229], v[16:17], v[228:229], v[142:143]
	v_add_f32_e32 v140, v226, v227
	v_add_f32_e32 v144, v228, v229
	s_nop 1
	v_permlane16_swap_b32_e32 v116, v120
	v_permlane16_swap_b32_e32 v124, v128
	v_permlane16_swap_b32_e32 v132, v136
	v_permlane16_swap_b32_e32 v140, v144
	v_add_f32_e32 v233, v116, v120
	v_add_f32_e32 v231, v124, v128
	v_add_f32_e32 v232, v132, v136
	v_add_f32_e32 v230, v140, v144
	s_nop 1
	v_permlane32_swap_b32_e32 v233, v231
	v_permlane32_swap_b32_e32 v232, v230
	v_pk_add_f32 v[230:231], v[232:233], v[230:231]
	v_pk_add_f32 v[230:231], v[230:231], 0 op_sel_hi:[1,0]
	v_ashrrev_i32_e32 v235, 31, v231
	v_ashrrev_i32_e32 v236, 31, v230
	v_or_b32_e32 v235, 0x80000000, v235
	v_or_b32_e32 v236, 0x80000000, v236
	v_xor_b32_e32 v235, v231, v235
	v_xor_b32_e32 v236, v230, v236
	v_cndmask_b32_e64 v235, 0, v235, s[90:91]
	v_cndmask_b32_e64 v236, 0, v236, s[92:93]
	ds_write_b32 v4, v235
	ds_write_b32 v237, v236
	s_sub_i32 s11, s9, 48
	s_cmp_ge_i32 s11, s6
	s_cbranch_scc1 .Lsc_exit
	s_cmp_lt_i32 s10, s6
	s_cbranch_scc1 .Lsc_w1n
	s_waitcnt vmcnt(4)
	s_branch .Lsc_m1

.Lsc_m1:
	v_mfma_f32_16x16x32_bf16 v[114:117], v[94:97], v[150:153], 0
	v_mfma_f32_16x16x32_bf16 v[118:121], v[82:85], v[150:153], 0
	v_mfma_f32_16x16x32_bf16 v[122:125], v[70:73], v[150:153], 0
	v_mfma_f32_16x16x32_bf16 v[126:129], v[58:61], v[150:153], 0
	v_mfma_f32_16x16x32_bf16 v[130:133], v[46:49], v[150:153], 0
	v_mfma_f32_16x16x32_bf16 v[134:137], v[34:37], v[150:153], 0
	v_mfma_f32_16x16x32_bf16 v[138:141], v[22:25], v[150:153], 0
	v_mfma_f32_16x16x32_bf16 v[142:145], v[10:13], v[150:153], 0
	v_mfma_f32_16x16x32_bf16 v[114:117], v[90:93], v[146:149], v[114:117]
	v_mfma_f32_16x16x32_bf16 v[118:121], v[78:81], v[146:149], v[118:121]
	v_mfma_f32_16x16x32_bf16 v[122:125], v[66:69], v[146:149], v[122:125]
	v_mfma_f32_16x16x32_bf16 v[126:129], v[54:57], v[146:149], v[126:129]
	v_add_u32_e32 v234, 0xffffff00, v5
	v_cmp_le_i32_e64 s[90:91], v234, v0
	v_cmp_le_i32_e64 s[92:93], v234, v223
	v_add_u32_e32 v237, 0x10200, v4
	s_nop 1
	v_max_i32_e32 v226, 0, v115
	v_max_i32_e32 v228, 0, v119
	v_max_i32_e32 v227, 0, v116
	v_max_i32_e32 v229, 0, v120
	v_mfma_f32_16x16x32_bf16 v[130:133], v[42:45], v[146:149], v[130:133]
	v_max_i32_e32 v115, 0, v117
	v_max_i32_e32 v119, 0, v121
	v_max_i32_e32 v114, 0, v114
	v_max_i32_e32 v118, 0, v118
	v_pk_mul_f32 v[114:115], v[86:87], v[114:115]
	v_pk_mul_f32 v[118:119], v[74:75], v[118:119]
	v_mfma_f32_16x16x32_bf16 v[134:137], v[30:33], v[146:149], v[134:137]
	v_pk_fma_f32 v[226:227], v[184:185], v[226:227], v[114:115]
	v_pk_fma_f32 v[228:229], v[88:89], v[228:229], v[118:119]
	v_add_f32_e32 v116, v226, v227
	v_add_f32_e32 v120, v228, v229
	v_max_i32_e32 v226, 0, v123
	v_max_i32_e32 v228, 0, v127
	v_max_i32_e32 v227, 0, v124
	v_max_i32_e32 v229, 0, v128
	v_mfma_f32_16x16x32_bf16 v[138:141], v[18:21], v[146:149], v[138:141]
	v_max_i32_e32 v123, 0, v125
	v_max_i32_e32 v127, 0, v129
	v_max_i32_e32 v122, 0, v122
	v_max_i32_e32 v126, 0, v126
	v_pk_mul_f32 v[122:123], v[62:63], v[122:123]
	v_pk_mul_f32 v[126:127], v[50:51], v[126:127]
	v_mfma_f32_16x16x32_bf16 v[142:145], v[6:9], v[146:149], v[142:145]
	v_pk_fma_f32 v[226:227], v[76:77], v[226:227], v[122:123]
	v_pk_fma_f32 v[228:229], v[64:65], v[228:229], v[126:127]
	v_add_f32_e32 v124, v226, v227
	v_add_f32_e32 v128, v228, v229
	s_cmp_lt_i32 s10, s6
	s_cbranch_scc0 .Lsc_np1
	s_add_i32 s11, s9, -16
	s_min_i32 s12, s11, s7
	s_ashr_i32 s13, s12, 31
	s_lshl_b64 s[12:13], s[12:13], 11
	v_lshl_add_u64 v[244:245], v[182:183], 0, s[12:13]
	global_load_dwordx4 v[150:153], v[244:245], off
	global_load_dwordx4 v[146:149], v[244:245], off offset:64
.Lsc_np1:
	v_max_i32_e32 v226, 0, v131
	v_max_i32_e32 v228, 0, v135
	v_max_i32_e32 v227, 0, v132
	v_max_i32_e32 v229, 0, v136
	v_max_i32_e32 v131, 0, v133
	v_max_i32_e32 v135, 0, v137
	v_max_i32_e32 v130, 0, v130
	v_max_i32_e32 v134, 0, v134
	v_pk_mul_f32 v[130:131], v[38:39], v[130:131]
	v_pk_mul_f32 v[134:135], v[26:27], v[134:135]
	v_pk_fma_f32 v[226:227], v[52:53], v[226:227], v[130:131]
	v_pk_fma_f32 v[228:229], v[40:41], v[228:229], v[134:135]
	v_add_f32_e32 v132, v226, v227
	v_add_f32_e32 v136, v228, v229
	v_max_i32_e32 v226, 0, v139
	v_max_i32_e32 v228, 0, v143
	v_max_i32_e32 v227, 0, v140
	v_max_i32_e32 v229, 0, v144
	v_max_i32_e32 v139, 0, v141
	v_max_i32_e32 v143, 0, v145
	v_max_i32_e32 v138, 0, v138
	v_max_i32_e32 v142, 0, v142
	v_pk_mul_f32 v[138:139], v[14:15], v[138:139]
	v_pk_mul_f32 v[142:143], v[2:3], v[142:143]
	v_pk_fma_f32 v[226:227], v[28:29], v[226:227], v[138:139]
	v_pk_fma_f32 v[228:229], v[16:17], v[228:229], v[142:143]
	v_add_f32_e32 v140, v226, v227
	v_add_f32_e32 v144, v228, v229
	s_nop 1
	v_permlane16_swap_b32_e32 v116, v120
	v_permlane16_swap_b32_e32 v124, v128
	v_permlane16_swap_b32_e32 v132, v136
	v_permlane16_swap_b32_e32 v140, v144
	v_add_f32_e32 v233, v116, v120
	v_add_f32_e32 v231, v124, v128
	v_add_f32_e32 v232, v132, v136
	v_add_f32_e32 v230, v140, v144
	s_nop 1
	v_permlane32_swap_b32_e32 v233, v231
	v_permlane32_swap_b32_e32 v232, v230
	v_pk_add_f32 v[230:231], v[232:233], v[230:231]
	v_pk_add_f32 v[230:231], v[230:231], 0 op_sel_hi:[1,0]
	v_ashrrev_i32_e32 v235, 31, v231
	v_ashrrev_i32_e32 v236, 31, v230
	v_or_b32_e32 v235, 0x80000000, v235
	v_or_b32_e32 v236, 0x80000000, v236
	v_xor_b32_e32 v235, v231, v235
	v_xor_b32_e32 v236, v230, v236
	v_cndmask_b32_e64 v235, 0, v235, s[90:91]
	v_cndmask_b32_e64 v236, 0, v236, s[92:93]
	ds_write_b32 v4, v235 offset:512
	ds_write_b32 v237, v236
	s_sub_i32 s11, s9, 40
	s_cmp_ge_i32 s11, s6
	s_cbranch_scc1 .Lsc_exit
	s_cmp_lt_i32 s10, s6
	s_cbranch_scc1 .Lsc_w2n
	s_waitcnt vmcnt(2)
	s_branch .Lsc_m2

.Lsc_m2:
	v_mfma_f32_16x16x32_bf16 v[114:117], v[94:97], v[110:113], 0
	v_mfma_f32_16x16x32_bf16 v[118:121], v[82:85], v[110:113], 0
	v_mfma_f32_16x16x32_bf16 v[122:125], v[70:73], v[110:113], 0
	v_mfma_f32_16x16x32_bf16 v[126:129], v[58:61], v[110:113], 0
	v_mfma_f32_16x16x32_bf16 v[130:133], v[46:49], v[110:113], 0
	v_mfma_f32_16x16x32_bf16 v[134:137], v[34:37], v[110:113], 0
	v_mfma_f32_16x16x32_bf16 v[138:141], v[22:25], v[110:113], 0
	v_mfma_f32_16x16x32_bf16 v[142:145], v[10:13], v[110:113], 0
	v_mfma_f32_16x16x32_bf16 v[114:117], v[90:93], v[106:109], v[114:117]
	v_mfma_f32_16x16x32_bf16 v[118:121], v[78:81], v[106:109], v[118:121]
	v_mfma_f32_16x16x32_bf16 v[122:125], v[66:69], v[106:109], v[122:125]
	v_mfma_f32_16x16x32_bf16 v[126:129], v[54:57], v[106:109], v[126:129]
	v_add_u32_e32 v234, 0xffffff80, v5
	v_cmp_le_i32_e64 s[90:91], v234, v0
	v_cmp_le_i32_e64 s[92:93], v234, v223
	v_add_u32_e32 v237, 0x10400, v4
	s_nop 1
	v_max_i32_e32 v226, 0, v115
	v_max_i32_e32 v228, 0, v119
	v_max_i32_e32 v227, 0, v116
	v_max_i32_e32 v229, 0, v120
	v_mfma_f32_16x16x32_bf16 v[130:133], v[42:45], v[106:109], v[130:133]
	v_max_i32_e32 v115, 0, v117
	v_max_i32_e32 v119, 0, v121
	v_max_i32_e32 v114, 0, v114
	v_max_i32_e32 v118, 0, v118
	v_pk_mul_f32 v[114:115], v[86:87], v[114:115]
	v_pk_mul_f32 v[118:119], v[74:75], v[118:119]
	v_mfma_f32_16x16x32_bf16 v[134:137], v[30:33], v[106:109], v[134:137]
	v_pk_fma_f32 v[226:227], v[184:185], v[226:227], v[114:115]
	v_pk_fma_f32 v[228:229], v[88:89], v[228:229], v[118:119]
	v_add_f32_e32 v116, v226, v227
	v_add_f32_e32 v120, v228, v229
	v_max_i32_e32 v226, 0, v123
	v_max_i32_e32 v228, 0, v127
	v_max_i32_e32 v227, 0, v124
	v_max_i32_e32 v229, 0, v128
	v_mfma_f32_16x16x32_bf16 v[138:141], v[18:21], v[106:109], v[138:141]
	v_max_i32_e32 v123, 0, v125
	v_max_i32_e32 v127, 0, v129
	v_max_i32_e32 v122, 0, v122
	v_max_i32_e32 v126, 0, v126
	v_pk_mul_f32 v[122:123], v[62:63], v[122:123]
	v_pk_mul_f32 v[126:127], v[50:51], v[126:127]
	v_mfma_f32_16x16x32_bf16 v[142:145], v[6:9], v[106:109], v[142:145]
	v_pk_fma_f32 v[226:227], v[76:77], v[226:227], v[122:123]
	v_pk_fma_f32 v[228:229], v[64:65], v[228:229], v[126:127]
	v_add_f32_e32 v124, v226, v227
	v_add_f32_e32 v128, v228, v229
	s_cmp_lt_i32 s10, s6
	s_cbranch_scc0 .Lsc_np2
	s_add_i32 s11, s9, -8
	s_min_i32 s12, s11, s7
	s_ashr_i32 s13, s12, 31
	s_lshl_b64 s[12:13], s[12:13], 11
	v_lshl_add_u64 v[244:245], v[182:183], 0, s[12:13]
	global_load_dwordx4 v[110:113], v[244:245], off
	global_load_dwordx4 v[106:109], v[244:245], off offset:64
.Lsc_np2:
	v_max_i32_e32 v226, 0, v131
	v_max_i32_e32 v228, 0, v135
	v_max_i32_e32 v227, 0, v132
	v_max_i32_e32 v229, 0, v136
	v_max_i32_e32 v131, 0, v133
	v_max_i32_e32 v135, 0, v137
	v_max_i32_e32 v130, 0, v130
	v_max_i32_e32 v134, 0, v134
	v_pk_mul_f32 v[130:131], v[38:39], v[130:131]
	v_pk_mul_f32 v[134:135], v[26:27], v[134:135]
	v_pk_fma_f32 v[226:227], v[52:53], v[226:227], v[130:131]
	v_pk_fma_f32 v[228:229], v[40:41], v[228:229], v[134:135]
	v_add_f32_e32 v132, v226, v227
	v_add_f32_e32 v136, v228, v229
	v_max_i32_e32 v226, 0, v139
	v_max_i32_e32 v228, 0, v143
	v_max_i32_e32 v227, 0, v140
	v_max_i32_e32 v229, 0, v144
	v_max_i32_e32 v139, 0, v141
	v_max_i32_e32 v143, 0, v145
	v_max_i32_e32 v138, 0, v138
	v_max_i32_e32 v142, 0, v142
	v_pk_mul_f32 v[138:139], v[14:15], v[138:139]
	v_pk_mul_f32 v[142:143], v[2:3], v[142:143]
	v_pk_fma_f32 v[226:227], v[28:29], v[226:227], v[138:139]
	v_pk_fma_f32 v[228:229], v[16:17], v[228:229], v[142:143]
	v_add_f32_e32 v140, v226, v227
	v_add_f32_e32 v144, v228, v229
	s_nop 1
	v_permlane16_swap_b32_e32 v116, v120
	v_permlane16_swap_b32_e32 v124, v128
	v_permlane16_swap_b32_e32 v132, v136
	v_permlane16_swap_b32_e32 v140, v144
	v_add_f32_e32 v233, v116, v120
	v_add_f32_e32 v231, v124, v128
	v_add_f32_e32 v232, v132, v136
	v_add_f32_e32 v230, v140, v144
	s_nop 1
	v_permlane32_swap_b32_e32 v233, v231
	v_permlane32_swap_b32_e32 v232, v230
	v_pk_add_f32 v[230:231], v[232:233], v[230:231]
	v_pk_add_f32 v[230:231], v[230:231], 0 op_sel_hi:[1,0]
	v_ashrrev_i32_e32 v235, 31, v231
	v_ashrrev_i32_e32 v236, 31, v230
	v_or_b32_e32 v235, 0x80000000, v235
	v_or_b32_e32 v236, 0x80000000, v236
	v_xor_b32_e32 v235, v231, v235
	v_xor_b32_e32 v236, v230, v236
	v_cndmask_b32_e64 v235, 0, v235, s[90:91]
	v_cndmask_b32_e64 v236, 0, v236, s[92:93]
	ds_write_b32 v4, v235 offset:1024
	ds_write_b32 v237, v236
	s_sub_i32 s11, s9, 32
	s_cmp_ge_i32 s11, s6
	s_cbranch_scc1 .Lsc_exit
	s_cmp_lt_i32 s10, s6
	s_cbranch_scc1 .Lsc_w3n
	s_waitcnt vmcnt(0)
	s_branch .Lsc_m3

.Lsc_m3:
	v_mfma_f32_16x16x32_bf16 v[114:117], v[94:97], v[102:105], 0
	v_mfma_f32_16x16x32_bf16 v[118:121], v[82:85], v[102:105], 0
	v_mfma_f32_16x16x32_bf16 v[122:125], v[70:73], v[102:105], 0
	v_mfma_f32_16x16x32_bf16 v[126:129], v[58:61], v[102:105], 0
	v_mfma_f32_16x16x32_bf16 v[130:133], v[46:49], v[102:105], 0
	v_mfma_f32_16x16x32_bf16 v[134:137], v[34:37], v[102:105], 0
	v_mfma_f32_16x16x32_bf16 v[138:141], v[22:25], v[102:105], 0
	v_mfma_f32_16x16x32_bf16 v[142:145], v[10:13], v[102:105], 0
	v_mfma_f32_16x16x32_bf16 v[114:117], v[90:93], v[98:101], v[114:117]
	v_mfma_f32_16x16x32_bf16 v[118:121], v[78:81], v[98:101], v[118:121]
	v_mfma_f32_16x16x32_bf16 v[122:125], v[66:69], v[98:101], v[122:125]
	v_mfma_f32_16x16x32_bf16 v[126:129], v[54:57], v[98:101], v[126:129]
	v_mov_b32_e32 v234, v5
	v_cmp_le_i32_e64 s[90:91], v234, v0
	v_cmp_le_i32_e64 s[92:93], v234, v223
	v_add_u32_e32 v237, 0x10600, v4
	s_nop 1
	v_max_i32_e32 v226, 0, v115
	v_max_i32_e32 v228, 0, v119
	v_max_i32_e32 v227, 0, v116
	v_max_i32_e32 v229, 0, v120
	v_mfma_f32_16x16x32_bf16 v[130:133], v[42:45], v[98:101], v[130:133]
	v_max_i32_e32 v115, 0, v117
	v_max_i32_e32 v119, 0, v121
	v_max_i32_e32 v114, 0, v114
	v_max_i32_e32 v118, 0, v118
	v_pk_mul_f32 v[114:115], v[86:87], v[114:115]
	v_pk_mul_f32 v[118:119], v[74:75], v[118:119]
	v_mfma_f32_16x16x32_bf16 v[134:137], v[30:33], v[98:101], v[134:137]
	v_pk_fma_f32 v[226:227], v[184:185], v[226:227], v[114:115]
	v_pk_fma_f32 v[228:229], v[88:89], v[228:229], v[118:119]
	v_add_f32_e32 v116, v226, v227
	v_add_f32_e32 v120, v228, v229
	v_max_i32_e32 v226, 0, v123
	v_max_i32_e32 v228, 0, v127
	v_max_i32_e32 v227, 0, v124
	v_max_i32_e32 v229, 0, v128
	v_mfma_f32_16x16x32_bf16 v[138:141], v[18:21], v[98:101], v[138:141]
	v_max_i32_e32 v123, 0, v125
	v_max_i32_e32 v127, 0, v129
	v_max_i32_e32 v122, 0, v122
	v_max_i32_e32 v126, 0, v126
	v_pk_mul_f32 v[122:123], v[62:63], v[122:123]
	v_pk_mul_f32 v[126:127], v[50:51], v[126:127]
	v_mfma_f32_16x16x32_bf16 v[142:145], v[6:9], v[98:101], v[142:145]
	v_pk_fma_f32 v[226:227], v[76:77], v[226:227], v[122:123]
	v_pk_fma_f32 v[228:229], v[64:65], v[228:229], v[126:127]
	v_add_f32_e32 v124, v226, v227
	v_add_f32_e32 v128, v228, v229
	s_cmp_lt_i32 s10, s6
	s_cbranch_scc0 .Lsc_np3
	s_add_i32 s11, s9, 0
	s_min_i32 s12, s11, s7
	s_ashr_i32 s13, s12, 31
	s_lshl_b64 s[12:13], s[12:13], 11
	v_lshl_add_u64 v[244:245], v[182:183], 0, s[12:13]
	global_load_dwordx4 v[102:105], v[244:245], off
	global_load_dwordx4 v[98:101], v[244:245], off offset:64
.Lsc_np3:
	v_max_i32_e32 v226, 0, v131
	v_max_i32_e32 v228, 0, v135
	v_max_i32_e32 v227, 0, v132
	v_max_i32_e32 v229, 0, v136
	v_max_i32_e32 v131, 0, v133
	v_max_i32_e32 v135, 0, v137
	v_max_i32_e32 v130, 0, v130
	v_max_i32_e32 v134, 0, v134
	v_pk_mul_f32 v[130:131], v[38:39], v[130:131]
	v_pk_mul_f32 v[134:135], v[26:27], v[134:135]
	v_pk_fma_f32 v[226:227], v[52:53], v[226:227], v[130:131]
	v_pk_fma_f32 v[228:229], v[40:41], v[228:229], v[134:135]
	v_add_f32_e32 v132, v226, v227
	v_add_f32_e32 v136, v228, v229
	v_max_i32_e32 v226, 0, v139
	v_max_i32_e32 v228, 0, v143
	v_max_i32_e32 v227, 0, v140
	v_max_i32_e32 v229, 0, v144
	v_max_i32_e32 v139, 0, v141
	v_max_i32_e32 v143, 0, v145
	v_max_i32_e32 v138, 0, v138
	v_max_i32_e32 v142, 0, v142
	v_pk_mul_f32 v[138:139], v[14:15], v[138:139]
	v_pk_mul_f32 v[142:143], v[2:3], v[142:143]
	v_pk_fma_f32 v[226:227], v[28:29], v[226:227], v[138:139]
	v_pk_fma_f32 v[228:229], v[16:17], v[228:229], v[142:143]
	v_add_f32_e32 v140, v226, v227
	v_add_f32_e32 v144, v228, v229
	s_nop 1
	v_permlane16_swap_b32_e32 v116, v120
	v_permlane16_swap_b32_e32 v124, v128
	v_permlane16_swap_b32_e32 v132, v136
	v_permlane16_swap_b32_e32 v140, v144
	v_add_f32_e32 v233, v116, v120
	v_add_f32_e32 v231, v124, v128
	v_add_f32_e32 v232, v132, v136
	v_add_f32_e32 v230, v140, v144
	s_nop 1
	v_permlane32_swap_b32_e32 v233, v231
	v_permlane32_swap_b32_e32 v232, v230
	v_pk_add_f32 v[230:231], v[232:233], v[230:231]
	v_pk_add_f32 v[230:231], v[230:231], 0 op_sel_hi:[1,0]
	v_ashrrev_i32_e32 v235, 31, v231
	v_ashrrev_i32_e32 v236, 31, v230
	v_or_b32_e32 v235, 0x80000000, v235
	v_or_b32_e32 v236, 0x80000000, v236
	v_xor_b32_e32 v235, v231, v235
	v_xor_b32_e32 v236, v230, v236
	v_cndmask_b32_e64 v235, 0, v235, s[90:91]
	v_cndmask_b32_e64 v236, 0, v236, s[92:93]
	ds_write_b32 v4, v235 offset:1536
	ds_write_b32 v237, v236
	s_add_i32 s9, s9, 32
	v_add_u32_e32 v4, 0x800, v4
	v_add_u32_e32 v5, 0x200, v5
	v_lshl_add_u64 v[180:181], v[180:181], 0, s[34:35]
	s_cmp_ge_i32 s10, s6
	s_cbranch_scc0 .Lsc_step
